# gate/up GEMM epilogue re-expressed with packed f32 ops on element pairs (same arithmetic, no packing moves, four pairs interleaved)
# speedup vs baseline: 1.0095x; 1.0047x over previous
; __device__ __forceinline__ unsigned cvt_pk_bf16(float lo, float hi) { unsigned r; asm volatile("v_cvt_pk_bf16_f32 %0, %1, %2" : "=v"(r) : "v"(lo), "v"(hi)); return r; }
;     __device__ __forceinline__ void operator()(const f32x4 (&acc)[2][2][4][2], const Unit& u, int wr, int wc, int fr, int fq) const {
;     ...
;         for (int ai = 0; ai < 2; ++ai)
; #pragma unroll
;             for (int m = 0; m < 4; ++m) { const int row = row0 + ai * HALF + m * 16; const float r = rs[ai * 4 + m];
;                 float hv[8];
; #pragma unroll
;                 for (int n = 0; n < 2; ++n)
; #pragma unroll
;                     for (int e = 0; e < 4; ++e) { const float g = acc[ai][0][m][n][e] * r, up = acc[ai][1][m][n][e] * r;
;                         const float sg = g * __builtin_amdgcn_rcpf(1.0f + __builtin_amdgcn_exp2f(g * -1.4426950408889634f)); hv[n * 4 + e] = sg * up; }
;                 u32x4 w; w.x = cvt_pk_bf16(hv[0], hv[1]); w.y = cvt_pk_bf16(hv[2], hv[3]); w.z = cvt_pk_bf16(hv[4], hv[5]); w.w = cvt_pk_bf16(hv[6], hv[7]);
;                 *(u32x4*)(H + (size_t)row * 2816 + col0) = w; }
.LBB0_104:
	s_mov_b32 s100, 0xbfb8aa3b
	s_mov_b32 s101, 1.0
	s_waitcnt lgkmcnt(0)
	v_pk_mul_f32 v[132:133], v[132:133], v[0:1] op_sel_hi:[1,0]
	v_pk_mul_f32 v[134:135], v[134:135], v[0:1] op_sel_hi:[1,0]
	v_pk_mul_f32 v[124:125], v[124:125], v[0:1] op_sel_hi:[1,0]
	v_pk_mul_f32 v[126:127], v[126:127], v[0:1] op_sel_hi:[1,0]
	v_pk_mul_f32 v[128:129], v[128:129], v[0:1] op_sel_hi:[1,0]
	v_pk_mul_f32 v[130:131], v[130:131], v[0:1] op_sel_hi:[1,0]
	v_pk_mul_f32 v[120:121], v[120:121], v[0:1] op_sel_hi:[1,0]
	v_pk_mul_f32 v[122:123], v[122:123], v[0:1] op_sel_hi:[1,0]
	v_pk_mul_f32 v[182:183], v[132:133], s[100:101] op_sel_hi:[1,0]
	v_pk_mul_f32 v[184:185], v[134:135], s[100:101] op_sel_hi:[1,0]
	v_pk_mul_f32 v[186:187], v[124:125], s[100:101] op_sel_hi:[1,0]
	v_pk_mul_f32 v[188:189], v[126:127], s[100:101] op_sel_hi:[1,0]
	v_exp_f32_e32 v182, v182
	v_exp_f32_e32 v183, v183
	v_exp_f32_e32 v184, v184
	v_exp_f32_e32 v185, v185
	v_exp_f32_e32 v186, v186
	v_exp_f32_e32 v187, v187
	v_exp_f32_e32 v188, v188
	v_exp_f32_e32 v189, v189
	v_pk_add_f32 v[182:183], v[182:183], s[100:101] op_sel:[0,1]
	v_pk_add_f32 v[184:185], v[184:185], s[100:101] op_sel:[0,1]
	v_pk_add_f32 v[186:187], v[186:187], s[100:101] op_sel:[0,1]
	v_pk_add_f32 v[188:189], v[188:189], s[100:101] op_sel:[0,1]
	v_rcp_f32_e32 v182, v182
	v_rcp_f32_e32 v183, v183
	v_rcp_f32_e32 v184, v184
	v_rcp_f32_e32 v185, v185
	v_rcp_f32_e32 v186, v186
	v_rcp_f32_e32 v187, v187
	v_rcp_f32_e32 v188, v188
	v_rcp_f32_e32 v189, v189
	v_pk_mul_f32 v[182:183], v[132:133], v[182:183]
	v_pk_mul_f32 v[184:185], v[134:135], v[184:185]
	v_pk_mul_f32 v[186:187], v[124:125], v[186:187]
	v_pk_mul_f32 v[188:189], v[126:127], v[188:189]
	v_pk_mul_f32 v[182:183], v[128:129], v[182:183]
	v_pk_mul_f32 v[184:185], v[130:131], v[184:185]
	v_pk_mul_f32 v[186:187], v[120:121], v[186:187]
	v_pk_mul_f32 v[188:189], v[122:123], v[188:189]
	v_cvt_pk_bf16_f32 v124, v182, v183
	v_cvt_pk_bf16_f32 v125, v184, v185
	v_cvt_pk_bf16_f32 v126, v186, v187
	v_cvt_pk_bf16_f32 v127, v188, v189
	v_lshl_or_b32 v176, s42, 7, v179
	v_ashrrev_i32_e32 v177, 31, v176
	s_andn2_b64 vcc, exec, s[4:5]
	v_mov_b64_e32 v[120:121], s[10:11]
	v_mad_u64_u32 v[128:129], s[22:23], v158, s91, v[120:121]
	v_mov_b32_e32 v122, v129
	v_mad_u64_u32 v[122:123], s[22:23], v159, s91, v[122:123]
	v_mov_b32_e32 v129, v122
	v_lshlrev_b64 v[122:123], 1, v[176:177]
	v_lshl_add_u64 v[128:129], v[128:129], 0, v[122:123]
	global_store_dwordx4 v[128:129], v[124:127], off
	s_nop 1
	v_pk_mul_f32 v[116:117], v[116:117], v[0:1] op_sel:[0,1]
	v_pk_mul_f32 v[118:119], v[118:119], v[0:1] op_sel:[0,1]
	v_pk_mul_f32 v[108:109], v[108:109], v[0:1] op_sel:[0,1]
	v_pk_mul_f32 v[110:111], v[110:111], v[0:1] op_sel:[0,1]
	v_pk_mul_f32 v[112:113], v[112:113], v[0:1] op_sel:[0,1]
	v_pk_mul_f32 v[114:115], v[114:115], v[0:1] op_sel:[0,1]
	v_pk_mul_f32 v[104:105], v[104:105], v[0:1] op_sel:[0,1]
	v_pk_mul_f32 v[106:107], v[106:107], v[0:1] op_sel:[0,1]
	v_pk_mul_f32 v[182:183], v[116:117], s[100:101] op_sel_hi:[1,0]
	v_pk_mul_f32 v[184:185], v[118:119], s[100:101] op_sel_hi:[1,0]
	v_pk_mul_f32 v[186:187], v[108:109], s[100:101] op_sel_hi:[1,0]
	v_pk_mul_f32 v[188:189], v[110:111], s[100:101] op_sel_hi:[1,0]
	v_exp_f32_e32 v182, v182
	v_exp_f32_e32 v183, v183
	v_exp_f32_e32 v184, v184
	v_exp_f32_e32 v185, v185
	v_exp_f32_e32 v186, v186
	v_exp_f32_e32 v187, v187
	v_exp_f32_e32 v188, v188
	v_exp_f32_e32 v189, v189
	v_pk_add_f32 v[182:183], v[182:183], s[100:101] op_sel:[0,1]
	v_pk_add_f32 v[184:185], v[184:185], s[100:101] op_sel:[0,1]
	v_pk_add_f32 v[186:187], v[186:187], s[100:101] op_sel:[0,1]
	v_pk_add_f32 v[188:189], v[188:189], s[100:101] op_sel:[0,1]
	v_rcp_f32_e32 v182, v182
	v_rcp_f32_e32 v183, v183
	v_rcp_f32_e32 v184, v184
	v_rcp_f32_e32 v185, v185
	v_rcp_f32_e32 v186, v186
	v_rcp_f32_e32 v187, v187
	v_rcp_f32_e32 v188, v188
	v_rcp_f32_e32 v189, v189
	v_pk_mul_f32 v[182:183], v[116:117], v[182:183]
	v_pk_mul_f32 v[184:185], v[118:119], v[184:185]
	v_pk_mul_f32 v[186:187], v[108:109], v[186:187]
	v_pk_mul_f32 v[188:189], v[110:111], v[188:189]
	v_pk_mul_f32 v[182:183], v[112:113], v[182:183]
	v_pk_mul_f32 v[184:185], v[114:115], v[184:185]
	v_pk_mul_f32 v[186:187], v[104:105], v[186:187]
	v_pk_mul_f32 v[188:189], v[106:107], v[188:189]
	v_cvt_pk_bf16_f32 v104, v182, v183
	v_cvt_pk_bf16_f32 v105, v184, v185
	v_cvt_pk_bf16_f32 v106, v186, v187
	v_cvt_pk_bf16_f32 v107, v188, v189
	v_mad_u64_u32 v[0:1], s[22:23], v156, s91, v[120:121]
	v_mov_b32_e32 v108, v1
	v_mad_u64_u32 v[108:109], s[22:23], v157, s91, v[108:109]
	v_mov_b32_e32 v1, v108
	v_lshl_add_u64 v[0:1], v[0:1], 0, v[122:123]
	global_store_dwordx4 v[0:1], v[104:107], off
	s_nop 1
	v_pk_mul_f32 v[100:101], v[100:101], v[2:3] op_sel_hi:[1,0]
	v_pk_mul_f32 v[102:103], v[102:103], v[2:3] op_sel_hi:[1,0]
	v_pk_mul_f32 v[92:93], v[92:93], v[2:3] op_sel_hi:[1,0]
	v_pk_mul_f32 v[94:95], v[94:95], v[2:3] op_sel_hi:[1,0]
	v_pk_mul_f32 v[96:97], v[96:97], v[2:3] op_sel_hi:[1,0]
	v_pk_mul_f32 v[98:99], v[98:99], v[2:3] op_sel_hi:[1,0]
	v_pk_mul_f32 v[88:89], v[88:89], v[2:3] op_sel_hi:[1,0]
	v_pk_mul_f32 v[90:91], v[90:91], v[2:3] op_sel_hi:[1,0]
	v_pk_mul_f32 v[182:183], v[100:101], s[100:101] op_sel_hi:[1,0]
	v_pk_mul_f32 v[184:185], v[102:103], s[100:101] op_sel_hi:[1,0]
	v_pk_mul_f32 v[186:187], v[92:93], s[100:101] op_sel_hi:[1,0]
	v_pk_mul_f32 v[188:189], v[94:95], s[100:101] op_sel_hi:[1,0]
	v_exp_f32_e32 v182, v182
	v_exp_f32_e32 v183, v183
	v_exp_f32_e32 v184, v184
	v_exp_f32_e32 v185, v185
	v_exp_f32_e32 v186, v186
	v_exp_f32_e32 v187, v187
	v_exp_f32_e32 v188, v188
	v_exp_f32_e32 v189, v189
	v_pk_add_f32 v[182:183], v[182:183], s[100:101] op_sel:[0,1]
; __device__ __forceinline__ unsigned cvt_pk_bf16(float lo, float hi) { unsigned r; asm volatile("v_cvt_pk_bf16_f32 %0, %1, %2" : "=v"(r) : "v"(lo), "v"(hi)); return r; }
;     __device__ __forceinline__ void operator()(const f32x4 (&acc)[2][2][4][2], const Unit& u, int wr, int wc, int fr, int fq) const {
;     ...
;         for (int ai = 0; ai < 2; ++ai)
; #pragma unroll
;             for (int m = 0; m < 4; ++m) { const int row = row0 + ai * HALF + m * 16; const float r = rs[ai * 4 + m];
;                 float hv[8];
; #pragma unroll
;                 for (int n = 0; n < 2; ++n)
; #pragma unroll
;                     for (int e = 0; e < 4; ++e) { const float g = acc[ai][0][m][n][e] * r, up = acc[ai][1][m][n][e] * r;
;                         const float sg = g * __builtin_amdgcn_rcpf(1.0f + __builtin_amdgcn_exp2f(g * -1.4426950408889634f)); hv[n * 4 + e] = sg * up; }
;                 u32x4 w; w.x = cvt_pk_bf16(hv[0], hv[1]); w.y = cvt_pk_bf16(hv[2], hv[3]); w.z = cvt_pk_bf16(hv[4], hv[5]); w.w = cvt_pk_bf16(hv[6], hv[7]);
;                 *(u32x4*)(H + (size_t)row * 2816 + col0) = w; }
	v_pk_add_f32 v[184:185], v[184:185], s[100:101] op_sel:[0,1]
	v_pk_add_f32 v[186:187], v[186:187], s[100:101] op_sel:[0,1]
	v_pk_add_f32 v[188:189], v[188:189], s[100:101] op_sel:[0,1]
	v_rcp_f32_e32 v182, v182
	v_rcp_f32_e32 v183, v183
	v_rcp_f32_e32 v184, v184
	v_rcp_f32_e32 v185, v185
	v_rcp_f32_e32 v186, v186
	v_rcp_f32_e32 v187, v187
	v_rcp_f32_e32 v188, v188
	v_rcp_f32_e32 v189, v189
	v_pk_mul_f32 v[182:183], v[100:101], v[182:183]
	v_pk_mul_f32 v[184:185], v[102:103], v[184:185]
	v_pk_mul_f32 v[186:187], v[92:93], v[186:187]
	v_pk_mul_f32 v[188:189], v[94:95], v[188:189]
	v_pk_mul_f32 v[182:183], v[96:97], v[182:183]
	v_pk_mul_f32 v[184:185], v[98:99], v[184:185]
	v_pk_mul_f32 v[186:187], v[88:89], v[186:187]
	v_pk_mul_f32 v[188:189], v[90:91], v[188:189]
	v_cvt_pk_bf16_f32 v88, v182, v183
	v_cvt_pk_bf16_f32 v89, v184, v185
	v_cvt_pk_bf16_f32 v90, v186, v187
	v_cvt_pk_bf16_f32 v91, v188, v189
	v_mad_u64_u32 v[0:1], s[22:23], v154, s91, v[120:121]
	v_mov_b32_e32 v2, v1
	v_mad_u64_u32 v[92:93], s[22:23], v155, s91, v[2:3]
	v_mov_b32_e32 v1, v92
	v_lshl_add_u64 v[0:1], v[0:1], 0, v[122:123]
	global_store_dwordx4 v[0:1], v[88:91], off
	s_nop 1
	v_pk_mul_f32 v[84:85], v[84:85], v[2:3] op_sel:[0,1]
	v_pk_mul_f32 v[86:87], v[86:87], v[2:3] op_sel:[0,1]
	v_pk_mul_f32 v[76:77], v[76:77], v[2:3] op_sel:[0,1]
	v_pk_mul_f32 v[78:79], v[78:79], v[2:3] op_sel:[0,1]
	v_pk_mul_f32 v[80:81], v[80:81], v[2:3] op_sel:[0,1]
	v_pk_mul_f32 v[82:83], v[82:83], v[2:3] op_sel:[0,1]
	v_pk_mul_f32 v[72:73], v[72:73], v[2:3] op_sel:[0,1]
	v_pk_mul_f32 v[74:75], v[74:75], v[2:3] op_sel:[0,1]
	v_pk_mul_f32 v[182:183], v[84:85], s[100:101] op_sel_hi:[1,0]
	v_pk_mul_f32 v[184:185], v[86:87], s[100:101] op_sel_hi:[1,0]
	v_pk_mul_f32 v[186:187], v[76:77], s[100:101] op_sel_hi:[1,0]
	v_pk_mul_f32 v[188:189], v[78:79], s[100:101] op_sel_hi:[1,0]
	v_exp_f32_e32 v182, v182
	v_exp_f32_e32 v183, v183
	v_exp_f32_e32 v184, v184
	v_exp_f32_e32 v185, v185
	v_exp_f32_e32 v186, v186
	v_exp_f32_e32 v187, v187
	v_exp_f32_e32 v188, v188
	v_exp_f32_e32 v189, v189
	v_pk_add_f32 v[182:183], v[182:183], s[100:101] op_sel:[0,1]
	v_pk_add_f32 v[184:185], v[184:185], s[100:101] op_sel:[0,1]
	v_pk_add_f32 v[186:187], v[186:187], s[100:101] op_sel:[0,1]
	v_pk_add_f32 v[188:189], v[188:189], s[100:101] op_sel:[0,1]
	v_rcp_f32_e32 v182, v182
	v_rcp_f32_e32 v183, v183
	v_rcp_f32_e32 v184, v184
	v_rcp_f32_e32 v185, v185
	v_rcp_f32_e32 v186, v186
	v_rcp_f32_e32 v187, v187
	v_rcp_f32_e32 v188, v188
	v_rcp_f32_e32 v189, v189
	v_pk_mul_f32 v[182:183], v[84:85], v[182:183]
	v_pk_mul_f32 v[184:185], v[86:87], v[184:185]
	v_pk_mul_f32 v[186:187], v[76:77], v[186:187]
	v_pk_mul_f32 v[188:189], v[78:79], v[188:189]
	v_pk_mul_f32 v[182:183], v[80:81], v[182:183]
	v_pk_mul_f32 v[184:185], v[82:83], v[184:185]
	v_pk_mul_f32 v[186:187], v[72:73], v[186:187]
	v_pk_mul_f32 v[188:189], v[74:75], v[188:189]
	v_cvt_pk_bf16_f32 v0, v182, v183
	v_cvt_pk_bf16_f32 v1, v184, v185
	v_cvt_pk_bf16_f32 v2, v186, v187
	v_cvt_pk_bf16_f32 v3, v188, v189
	v_mad_u64_u32 v[72:73], s[22:23], v152, s91, v[120:121]
	v_mov_b32_e32 v74, v73
	v_mad_u64_u32 v[74:75], s[22:23], v153, s91, v[74:75]
	v_mov_b32_e32 v73, v74
	v_lshl_add_u64 v[72:73], v[72:73], 0, v[122:123]
	global_store_dwordx4 v[72:73], v[0:3], off
	s_nop 1
	v_pk_mul_f32 v[68:69], v[68:69], v[4:5] op_sel_hi:[1,0]
	v_pk_mul_f32 v[70:71], v[70:71], v[4:5] op_sel_hi:[1,0]
	v_pk_mul_f32 v[60:61], v[60:61], v[4:5] op_sel_hi:[1,0]
	v_pk_mul_f32 v[62:63], v[62:63], v[4:5] op_sel_hi:[1,0]
	v_pk_mul_f32 v[64:65], v[64:65], v[4:5] op_sel_hi:[1,0]
	v_pk_mul_f32 v[66:67], v[66:67], v[4:5] op_sel_hi:[1,0]
	v_pk_mul_f32 v[56:57], v[56:57], v[4:5] op_sel_hi:[1,0]
	v_pk_mul_f32 v[58:59], v[58:59], v[4:5] op_sel_hi:[1,0]
	v_pk_mul_f32 v[182:183], v[68:69], s[100:101] op_sel_hi:[1,0]
	v_pk_mul_f32 v[184:185], v[70:71], s[100:101] op_sel_hi:[1,0]
	v_pk_mul_f32 v[186:187], v[60:61], s[100:101] op_sel_hi:[1,0]
	v_pk_mul_f32 v[188:189], v[62:63], s[100:101] op_sel_hi:[1,0]
	v_exp_f32_e32 v182, v182
	v_exp_f32_e32 v183, v183
	v_exp_f32_e32 v184, v184
	v_exp_f32_e32 v185, v185
	v_exp_f32_e32 v186, v186
	v_exp_f32_e32 v187, v187
	v_exp_f32_e32 v188, v188
	v_exp_f32_e32 v189, v189
	v_pk_add_f32 v[182:183], v[182:183], s[100:101] op_sel:[0,1]
	v_pk_add_f32 v[184:185], v[184:185], s[100:101] op_sel:[0,1]
	v_pk_add_f32 v[186:187], v[186:187], s[100:101] op_sel:[0,1]
	v_pk_add_f32 v[188:189], v[188:189], s[100:101] op_sel:[0,1]
	v_rcp_f32_e32 v182, v182
	v_rcp_f32_e32 v183, v183
	v_rcp_f32_e32 v184, v184
	v_rcp_f32_e32 v185, v185
	v_rcp_f32_e32 v186, v186
	v_rcp_f32_e32 v187, v187
	v_rcp_f32_e32 v188, v188
	v_rcp_f32_e32 v189, v189
	v_pk_mul_f32 v[182:183], v[68:69], v[182:183]
	v_pk_mul_f32 v[184:185], v[70:71], v[184:185]
	v_pk_mul_f32 v[186:187], v[60:61], v[186:187]
	v_pk_mul_f32 v[188:189], v[62:63], v[188:189]
	v_pk_mul_f32 v[182:183], v[64:65], v[182:183]
	v_pk_mul_f32 v[184:185], v[66:67], v[184:185]
	v_pk_mul_f32 v[186:187], v[56:57], v[186:187]
	v_pk_mul_f32 v[188:189], v[58:59], v[188:189]
	v_cvt_pk_bf16_f32 v0, v182, v183
	v_cvt_pk_bf16_f32 v1, v184, v185
	v_cvt_pk_bf16_f32 v2, v186, v187
	v_cvt_pk_bf16_f32 v3, v188, v189
	v_mad_u64_u32 v[56:57], s[22:23], v150, s91, v[120:121]
	v_mov_b32_e32 v4, v57
	v_mad_u64_u32 v[58:59], s[22:23], v151, s91, v[4:5]
	v_mov_b32_e32 v57, v58
	v_lshl_add_u64 v[56:57], v[56:57], 0, v[122:123]
	global_store_dwordx4 v[56:57], v[0:3], off
	s_nop 1
	v_pk_mul_f32 v[52:53], v[52:53], v[4:5] op_sel:[0,1]
	v_pk_mul_f32 v[54:55], v[54:55], v[4:5] op_sel:[0,1]
	v_pk_mul_f32 v[44:45], v[44:45], v[4:5] op_sel:[0,1]
	v_pk_mul_f32 v[46:47], v[46:47], v[4:5] op_sel:[0,1]
; __device__ __forceinline__ unsigned cvt_pk_bf16(float lo, float hi) { unsigned r; asm volatile("v_cvt_pk_bf16_f32 %0, %1, %2" : "=v"(r) : "v"(lo), "v"(hi)); return r; }
;     __device__ __forceinline__ void operator()(const f32x4 (&acc)[2][2][4][2], const Unit& u, int wr, int wc, int fr, int fq) const {
;     ...
;             for (int m = 0; m < 4; ++m) { const int row = row0 + ai * HALF + m * 16; const float r = rs[ai * 4 + m];
;                 float hv[8];
; #pragma unroll
;                 for (int n = 0; n < 2; ++n)
; #pragma unroll
;                     for (int e = 0; e < 4; ++e) { const float g = acc[ai][0][m][n][e] * r, up = acc[ai][1][m][n][e] * r;
;                         const float sg = g * __builtin_amdgcn_rcpf(1.0f + __builtin_amdgcn_exp2f(g * -1.4426950408889634f)); hv[n * 4 + e] = sg * up; }
;                 u32x4 w; w.x = cvt_pk_bf16(hv[0], hv[1]); w.y = cvt_pk_bf16(hv[2], hv[3]); w.z = cvt_pk_bf16(hv[4], hv[5]); w.w = cvt_pk_bf16(hv[6], hv[7]);
;                 *(u32x4*)(H + (size_t)row * 2816 + col0) = w; }
	v_pk_mul_f32 v[48:49], v[48:49], v[4:5] op_sel:[0,1]
	v_pk_mul_f32 v[50:51], v[50:51], v[4:5] op_sel:[0,1]
	v_pk_mul_f32 v[40:41], v[40:41], v[4:5] op_sel:[0,1]
	v_pk_mul_f32 v[42:43], v[42:43], v[4:5] op_sel:[0,1]
	v_pk_mul_f32 v[182:183], v[52:53], s[100:101] op_sel_hi:[1,0]
	v_pk_mul_f32 v[184:185], v[54:55], s[100:101] op_sel_hi:[1,0]
	v_pk_mul_f32 v[186:187], v[44:45], s[100:101] op_sel_hi:[1,0]
	v_pk_mul_f32 v[188:189], v[46:47], s[100:101] op_sel_hi:[1,0]
	v_exp_f32_e32 v182, v182
	v_exp_f32_e32 v183, v183
	v_exp_f32_e32 v184, v184
	v_exp_f32_e32 v185, v185
	v_exp_f32_e32 v186, v186
	v_exp_f32_e32 v187, v187
	v_exp_f32_e32 v188, v188
	v_exp_f32_e32 v189, v189
	v_pk_add_f32 v[182:183], v[182:183], s[100:101] op_sel:[0,1]
	v_pk_add_f32 v[184:185], v[184:185], s[100:101] op_sel:[0,1]
	v_pk_add_f32 v[186:187], v[186:187], s[100:101] op_sel:[0,1]
	v_pk_add_f32 v[188:189], v[188:189], s[100:101] op_sel:[0,1]
	v_rcp_f32_e32 v182, v182
	v_rcp_f32_e32 v183, v183
	v_rcp_f32_e32 v184, v184
	v_rcp_f32_e32 v185, v185
	v_rcp_f32_e32 v186, v186
	v_rcp_f32_e32 v187, v187
	v_rcp_f32_e32 v188, v188
	v_rcp_f32_e32 v189, v189
	v_pk_mul_f32 v[182:183], v[52:53], v[182:183]
	v_pk_mul_f32 v[184:185], v[54:55], v[184:185]
	v_pk_mul_f32 v[186:187], v[44:45], v[186:187]
	v_pk_mul_f32 v[188:189], v[46:47], v[188:189]
	v_pk_mul_f32 v[182:183], v[48:49], v[182:183]
	v_pk_mul_f32 v[184:185], v[50:51], v[184:185]
	v_pk_mul_f32 v[186:187], v[40:41], v[186:187]
	v_pk_mul_f32 v[188:189], v[42:43], v[188:189]
	v_cvt_pk_bf16_f32 v0, v182, v183
	v_cvt_pk_bf16_f32 v1, v184, v185
	v_cvt_pk_bf16_f32 v2, v186, v187
	v_cvt_pk_bf16_f32 v3, v188, v189
	v_add_u32_e32 v44, 16, v148
	v_mad_i64_i32 v[4:5], s[22:23], v44, s91, v[120:121]
	v_lshl_add_u64 v[4:5], v[4:5], 0, v[122:123]
	global_store_dwordx4 v[4:5], v[0:3], off
	s_nop 1
	v_pk_mul_f32 v[36:37], v[36:37], v[6:7] op_sel_hi:[1,0]
	v_pk_mul_f32 v[38:39], v[38:39], v[6:7] op_sel_hi:[1,0]
	v_pk_mul_f32 v[28:29], v[28:29], v[6:7] op_sel_hi:[1,0]
	v_pk_mul_f32 v[30:31], v[30:31], v[6:7] op_sel_hi:[1,0]
	v_pk_mul_f32 v[32:33], v[32:33], v[6:7] op_sel_hi:[1,0]
	v_pk_mul_f32 v[34:35], v[34:35], v[6:7] op_sel_hi:[1,0]
	v_pk_mul_f32 v[24:25], v[24:25], v[6:7] op_sel_hi:[1,0]
	v_pk_mul_f32 v[26:27], v[26:27], v[6:7] op_sel_hi:[1,0]
	v_pk_mul_f32 v[182:183], v[36:37], s[100:101] op_sel_hi:[1,0]
	v_pk_mul_f32 v[184:185], v[38:39], s[100:101] op_sel_hi:[1,0]
	v_pk_mul_f32 v[186:187], v[28:29], s[100:101] op_sel_hi:[1,0]
	v_pk_mul_f32 v[188:189], v[30:31], s[100:101] op_sel_hi:[1,0]
	v_exp_f32_e32 v182, v182
	v_exp_f32_e32 v183, v183
	v_exp_f32_e32 v184, v184
	v_exp_f32_e32 v185, v185
	v_exp_f32_e32 v186, v186
	v_exp_f32_e32 v187, v187
	v_exp_f32_e32 v188, v188
	v_exp_f32_e32 v189, v189
	v_pk_add_f32 v[182:183], v[182:183], s[100:101] op_sel:[0,1]
	v_pk_add_f32 v[184:185], v[184:185], s[100:101] op_sel:[0,1]
	v_pk_add_f32 v[186:187], v[186:187], s[100:101] op_sel:[0,1]
	v_pk_add_f32 v[188:189], v[188:189], s[100:101] op_sel:[0,1]
	v_rcp_f32_e32 v182, v182
	v_rcp_f32_e32 v183, v183
	v_rcp_f32_e32 v184, v184
	v_rcp_f32_e32 v185, v185
	v_rcp_f32_e32 v186, v186
	v_rcp_f32_e32 v187, v187
	v_rcp_f32_e32 v188, v188
	v_rcp_f32_e32 v189, v189
	v_pk_mul_f32 v[182:183], v[36:37], v[182:183]
	v_pk_mul_f32 v[184:185], v[38:39], v[184:185]
	v_pk_mul_f32 v[186:187], v[28:29], v[186:187]
	v_pk_mul_f32 v[188:189], v[30:31], v[188:189]
	v_pk_mul_f32 v[182:183], v[32:33], v[182:183]
	v_pk_mul_f32 v[184:185], v[34:35], v[184:185]
	v_pk_mul_f32 v[186:187], v[24:25], v[186:187]
	v_pk_mul_f32 v[188:189], v[26:27], v[188:189]
	v_cvt_pk_bf16_f32 v0, v182, v183
	v_cvt_pk_bf16_f32 v1, v184, v185
	v_cvt_pk_bf16_f32 v2, v186, v187
	v_cvt_pk_bf16_f32 v3, v188, v189
	v_add_u32_e32 v27, 32, v148
	v_mad_i64_i32 v[4:5], s[22:23], v27, s91, v[120:121]
	v_lshl_add_u64 v[4:5], v[4:5], 0, v[122:123]
	global_store_dwordx4 v[4:5], v[0:3], off
	s_nop 1
	v_pk_mul_f32 v[20:21], v[20:21], v[6:7] op_sel:[0,1]
	v_pk_mul_f32 v[22:23], v[22:23], v[6:7] op_sel:[0,1]
	v_pk_mul_f32 v[12:13], v[12:13], v[6:7] op_sel:[0,1]
	v_pk_mul_f32 v[14:15], v[14:15], v[6:7] op_sel:[0,1]
	v_pk_mul_f32 v[16:17], v[16:17], v[6:7] op_sel:[0,1]
	v_pk_mul_f32 v[18:19], v[18:19], v[6:7] op_sel:[0,1]
	v_pk_mul_f32 v[8:9], v[8:9], v[6:7] op_sel:[0,1]
	v_pk_mul_f32 v[10:11], v[10:11], v[6:7] op_sel:[0,1]
	v_pk_mul_f32 v[182:183], v[20:21], s[100:101] op_sel_hi:[1,0]
	v_pk_mul_f32 v[184:185], v[22:23], s[100:101] op_sel_hi:[1,0]
	v_pk_mul_f32 v[186:187], v[12:13], s[100:101] op_sel_hi:[1,0]
	v_pk_mul_f32 v[188:189], v[14:15], s[100:101] op_sel_hi:[1,0]
	v_exp_f32_e32 v182, v182
	v_exp_f32_e32 v183, v183
	v_exp_f32_e32 v184, v184
	v_exp_f32_e32 v185, v185
	v_exp_f32_e32 v186, v186
	v_exp_f32_e32 v187, v187
	v_exp_f32_e32 v188, v188
	v_exp_f32_e32 v189, v189
	v_pk_add_f32 v[182:183], v[182:183], s[100:101] op_sel:[0,1]
	v_pk_add_f32 v[184:185], v[184:185], s[100:101] op_sel:[0,1]
	v_pk_add_f32 v[186:187], v[186:187], s[100:101] op_sel:[0,1]
	v_pk_add_f32 v[188:189], v[188:189], s[100:101] op_sel:[0,1]
	v_rcp_f32_e32 v182, v182
	v_rcp_f32_e32 v183, v183
	v_rcp_f32_e32 v184, v184
	v_rcp_f32_e32 v185, v185
	v_rcp_f32_e32 v186, v186
	v_rcp_f32_e32 v187, v187
	v_rcp_f32_e32 v188, v188
	v_rcp_f32_e32 v189, v189
	v_pk_mul_f32 v[182:183], v[20:21], v[182:183]
	v_pk_mul_f32 v[184:185], v[22:23], v[184:185]
	v_pk_mul_f32 v[186:187], v[12:13], v[186:187]
	v_pk_mul_f32 v[188:189], v[14:15], v[188:189]
	v_pk_mul_f32 v[182:183], v[16:17], v[182:183]
	v_pk_mul_f32 v[184:185], v[18:19], v[184:185]
	v_pk_mul_f32 v[186:187], v[8:9], v[186:187]
	v_pk_mul_f32 v[188:189], v[10:11], v[188:189]
	v_cvt_pk_bf16_f32 v0, v182, v183
	v_cvt_pk_bf16_f32 v1, v184, v185
	v_cvt_pk_bf16_f32 v2, v186, v187
	v_cvt_pk_bf16_f32 v3, v188, v189
	v_add_u32_e32 v11, 48, v148
	v_mad_i64_i32 v[4:5], s[22:23], v11, s91, v[120:121]
	v_lshl_add_u64 v[4:5], v[4:5], 0, v[122:123]
	s_mov_b64 s[22:23], -1
	global_store_dwordx4 v[4:5], v[0:3], off
	s_nop 1
	s_cbranch_vccnz .LBB0_93
	s_andn2_b64 vcc, exec, s[8:9]
	s_cbranch_vccnz .LBB0_92
	s_barrier
	s_branch .LBB0_92
